# SwiGLU epilogue written by hand: packed f32 math for the non-transcendental steps, no padding nops, pointer walks by the row pitch (476 -> 334 instructions per tile-wave, same operation order per elem
# speedup vs baseline: 1.0076x; 1.0022x over previous
; __device__ __forceinline__ unsigned pk2(float lo, float hi) { const f32x2 v = {lo, hi}; const bf16x2n b = __builtin_convertvector(v, bf16x2n); return __builtin_bit_cast(unsigned, b); }
; __device__ __forceinline__ float siluf_(float x) { return x * rcp_(1.0f + __expf(-x)); }
;     __device__ __forceinline__ void operator()(const f32x4 (&acc)[2][2][4][2], const Unit& u, int wr, int wc, int fr, int fq) const {
;     ...
;                 bf16_t* rowp = H + (size_t)(row0 + ai * 128 + m * 16) * DFF + col0;
;                 const f32x4 g0 = acc[ai][0][m][0], g1 = acc[ai][0][m][1], u0 = acc[ai][1][m][0], u1 = acc[ai][1][m][1];
;                 float v[8];
; #pragma unroll
;                 for (int j = 0; j < 4; ++j) { v[j] = siluf_(g0[j]) * u0[j]; v[4 + j] = siluf_(g1[j]) * u1[j]; }
;                 u32x4 w; w.x = pk2(v[0], v[1]); w.y = pk2(v[2], v[3]); w.z = pk2(v[4], v[5]); w.w = pk2(v[6], v[7]);
;                 __builtin_nontemporal_store(w, (u32x4*)rowp);
.LBB0_787:
	v_lshl_or_b32 v148, s25, 7, v144
	v_lshl_add_u32 v146, s24, 8, v142
	v_ashrrev_i32_e32 v149, 31, v148
	v_mov_b64_e32 v[140:141], s[94:95]
	v_mov_b32_e32 v176, 0xbfb8aa3b
	v_lshlrev_b64 v[148:149], 1, v[148:149]
	v_mad_i64_i32 v[150:151], s[24:25], v146, s67, v[140:141]
	s_nop 4
	v_lshl_add_u64 v[150:151], v[150:151], 0, v[148:149]
	s_mov_b64 s[24:25], 0x16000
	v_pk_mul_f32 v[152:153], v[126:127], v[176:177] op_sel_hi:[1,0]
	v_pk_mul_f32 v[154:155], v[128:129], v[176:177] op_sel_hi:[1,0]
	v_pk_mul_f32 v[156:157], v[118:119], v[176:177] op_sel_hi:[1,0]
	v_pk_mul_f32 v[158:159], v[120:121], v[176:177] op_sel_hi:[1,0]
	v_exp_f32_e32 v152, v152
	v_exp_f32_e32 v153, v153
	v_exp_f32_e32 v154, v154
	v_exp_f32_e32 v155, v155
	v_pk_add_f32 v[152:153], v[152:153], 1.0 op_sel_hi:[1,0]
	v_exp_f32_e32 v156, v156
	v_exp_f32_e32 v157, v157
	v_pk_add_f32 v[154:155], v[154:155], 1.0 op_sel_hi:[1,0]
	v_exp_f32_e32 v158, v158
	v_exp_f32_e32 v159, v159
	v_rcp_f32_e32 v152, v152
	v_pk_add_f32 v[156:157], v[156:157], 1.0 op_sel_hi:[1,0]
	v_rcp_f32_e32 v153, v153
	v_rcp_f32_e32 v154, v154
	v_pk_add_f32 v[158:159], v[158:159], 1.0 op_sel_hi:[1,0]
	v_rcp_f32_e32 v155, v155
	v_rcp_f32_e32 v156, v156
	v_pk_mul_f32 v[126:127], v[126:127], v[152:153]
	v_rcp_f32_e32 v157, v157
	v_rcp_f32_e32 v158, v158
	v_pk_mul_f32 v[128:129], v[128:129], v[154:155]
	v_rcp_f32_e32 v159, v159
	v_pk_mul_f32 v[126:127], v[126:127], v[122:123]
	v_pk_mul_f32 v[118:119], v[118:119], v[156:157]
	v_pk_mul_f32 v[128:129], v[128:129], v[124:125]
	s_nop 0
	v_pk_mul_f32 v[120:121], v[120:121], v[158:159]
	v_cvt_pk_bf16_f32 v168, v126, v127
	v_pk_mul_f32 v[118:119], v[118:119], v[114:115]
	v_cvt_pk_bf16_f32 v169, v128, v129
	v_pk_mul_f32 v[120:121], v[120:121], v[116:117]
	s_nop 0
	v_cvt_pk_bf16_f32 v170, v118, v119
	s_nop 0
	v_cvt_pk_bf16_f32 v171, v120, v121
	global_store_dwordx4 v[150:151], v[168:171], off nt
	v_pk_mul_f32 v[160:161], v[110:111], v[176:177] op_sel_hi:[1,0]
	v_pk_mul_f32 v[162:163], v[112:113], v[176:177] op_sel_hi:[1,0]
	v_pk_mul_f32 v[164:165], v[102:103], v[176:177] op_sel_hi:[1,0]
	v_pk_mul_f32 v[166:167], v[104:105], v[176:177] op_sel_hi:[1,0]
	v_exp_f32_e32 v160, v160
	v_exp_f32_e32 v161, v161
	v_exp_f32_e32 v162, v162
	v_exp_f32_e32 v163, v163
	v_pk_add_f32 v[160:161], v[160:161], 1.0 op_sel_hi:[1,0]
	v_exp_f32_e32 v164, v164
	v_exp_f32_e32 v165, v165
	v_pk_add_f32 v[162:163], v[162:163], 1.0 op_sel_hi:[1,0]
	v_exp_f32_e32 v166, v166
	v_exp_f32_e32 v167, v167
	v_rcp_f32_e32 v160, v160
	v_pk_add_f32 v[164:165], v[164:165], 1.0 op_sel_hi:[1,0]
	v_rcp_f32_e32 v161, v161
	v_rcp_f32_e32 v162, v162
	v_pk_add_f32 v[166:167], v[166:167], 1.0 op_sel_hi:[1,0]
	v_rcp_f32_e32 v163, v163
	v_rcp_f32_e32 v164, v164
	v_pk_mul_f32 v[110:111], v[110:111], v[160:161]
	v_rcp_f32_e32 v165, v165
	v_rcp_f32_e32 v166, v166
	v_pk_mul_f32 v[112:113], v[112:113], v[162:163]
	v_rcp_f32_e32 v167, v167
	v_pk_mul_f32 v[110:111], v[110:111], v[106:107]
	v_pk_mul_f32 v[102:103], v[102:103], v[164:165]
	v_pk_mul_f32 v[112:113], v[112:113], v[108:109]
	v_lshl_add_u64 v[178:179], v[150:151], 0, s[24:25]
	v_pk_mul_f32 v[104:105], v[104:105], v[166:167]
	v_cvt_pk_bf16_f32 v172, v110, v111
	v_pk_mul_f32 v[102:103], v[102:103], v[98:99]
	v_cvt_pk_bf16_f32 v173, v112, v113
	v_pk_mul_f32 v[104:105], v[104:105], v[100:101]
	s_nop 0
	v_cvt_pk_bf16_f32 v174, v102, v103
	s_nop 0
	v_cvt_pk_bf16_f32 v175, v104, v105
	global_store_dwordx4 v[178:179], v[172:175], off nt
	v_pk_mul_f32 v[152:153], v[94:95], v[176:177] op_sel_hi:[1,0]
	v_pk_mul_f32 v[154:155], v[96:97], v[176:177] op_sel_hi:[1,0]
	v_pk_mul_f32 v[156:157], v[86:87], v[176:177] op_sel_hi:[1,0]
	v_pk_mul_f32 v[158:159], v[88:89], v[176:177] op_sel_hi:[1,0]
	v_exp_f32_e32 v152, v152
	v_exp_f32_e32 v153, v153
	v_exp_f32_e32 v154, v154
	v_exp_f32_e32 v155, v155
	v_pk_add_f32 v[152:153], v[152:153], 1.0 op_sel_hi:[1,0]
	v_exp_f32_e32 v156, v156
	v_exp_f32_e32 v157, v157
	v_pk_add_f32 v[154:155], v[154:155], 1.0 op_sel_hi:[1,0]
	v_exp_f32_e32 v158, v158
	v_exp_f32_e32 v159, v159
	v_rcp_f32_e32 v152, v152
	v_pk_add_f32 v[156:157], v[156:157], 1.0 op_sel_hi:[1,0]
	v_rcp_f32_e32 v153, v153
	v_rcp_f32_e32 v154, v154
	v_pk_add_f32 v[158:159], v[158:159], 1.0 op_sel_hi:[1,0]
	v_rcp_f32_e32 v155, v155
	v_rcp_f32_e32 v156, v156
	v_pk_mul_f32 v[94:95], v[94:95], v[152:153]
	v_rcp_f32_e32 v157, v157
	v_rcp_f32_e32 v158, v158
	v_pk_mul_f32 v[96:97], v[96:97], v[154:155]
	v_rcp_f32_e32 v159, v159
	v_pk_mul_f32 v[94:95], v[94:95], v[90:91]
	v_pk_mul_f32 v[86:87], v[86:87], v[156:157]
	v_pk_mul_f32 v[96:97], v[96:97], v[92:93]
	v_lshl_add_u64 v[150:151], v[178:179], 0, s[24:25]
	v_pk_mul_f32 v[88:89], v[88:89], v[158:159]
	v_cvt_pk_bf16_f32 v168, v94, v95
	v_pk_mul_f32 v[86:87], v[86:87], v[82:83]
	v_cvt_pk_bf16_f32 v169, v96, v97
	v_pk_mul_f32 v[88:89], v[88:89], v[84:85]
	s_nop 0
	v_cvt_pk_bf16_f32 v170, v86, v87
	s_nop 0
	v_cvt_pk_bf16_f32 v171, v88, v89
	global_store_dwordx4 v[150:151], v[168:171], off nt
	v_pk_mul_f32 v[160:161], v[78:79], v[176:177] op_sel_hi:[1,0]
	v_pk_mul_f32 v[162:163], v[80:81], v[176:177] op_sel_hi:[1,0]
	v_pk_mul_f32 v[164:165], v[70:71], v[176:177] op_sel_hi:[1,0]
	v_pk_mul_f32 v[166:167], v[72:73], v[176:177] op_sel_hi:[1,0]
	v_exp_f32_e32 v160, v160
	v_exp_f32_e32 v161, v161
	v_exp_f32_e32 v162, v162
	v_exp_f32_e32 v163, v163
	v_pk_add_f32 v[160:161], v[160:161], 1.0 op_sel_hi:[1,0]
	v_exp_f32_e32 v164, v164
	v_exp_f32_e32 v165, v165
	v_pk_add_f32 v[162:163], v[162:163], 1.0 op_sel_hi:[1,0]
	v_exp_f32_e32 v166, v166
	v_exp_f32_e32 v167, v167
	v_rcp_f32_e32 v160, v160
	v_pk_add_f32 v[164:165], v[164:165], 1.0 op_sel_hi:[1,0]
; __device__ __forceinline__ unsigned pk2(float lo, float hi) { const f32x2 v = {lo, hi}; const bf16x2n b = __builtin_convertvector(v, bf16x2n); return __builtin_bit_cast(unsigned, b); }
; __device__ __forceinline__ float siluf_(float x) { return x * rcp_(1.0f + __expf(-x)); }
;     __device__ __forceinline__ void operator()(const f32x4 (&acc)[2][2][4][2], const Unit& u, int wr, int wc, int fr, int fq) const {
;     ...
;                 bf16_t* rowp = H + (size_t)(row0 + ai * 128 + m * 16) * DFF + col0;
;                 const f32x4 g0 = acc[ai][0][m][0], g1 = acc[ai][0][m][1], u0 = acc[ai][1][m][0], u1 = acc[ai][1][m][1];
;                 float v[8];
; #pragma unroll
;                 for (int j = 0; j < 4; ++j) { v[j] = siluf_(g0[j]) * u0[j]; v[4 + j] = siluf_(g1[j]) * u1[j]; }
;                 u32x4 w; w.x = pk2(v[0], v[1]); w.y = pk2(v[2], v[3]); w.z = pk2(v[4], v[5]); w.w = pk2(v[6], v[7]);
;                 __builtin_nontemporal_store(w, (u32x4*)rowp);
	v_rcp_f32_e32 v161, v161
	v_rcp_f32_e32 v162, v162
	v_pk_add_f32 v[166:167], v[166:167], 1.0 op_sel_hi:[1,0]
	v_rcp_f32_e32 v163, v163
	v_rcp_f32_e32 v164, v164
	v_pk_mul_f32 v[78:79], v[78:79], v[160:161]
	v_rcp_f32_e32 v165, v165
	v_rcp_f32_e32 v166, v166
	v_pk_mul_f32 v[80:81], v[80:81], v[162:163]
	v_rcp_f32_e32 v167, v167
	v_pk_mul_f32 v[78:79], v[78:79], v[74:75]
	v_pk_mul_f32 v[70:71], v[70:71], v[164:165]
	v_pk_mul_f32 v[80:81], v[80:81], v[76:77]
	v_lshl_add_u64 v[178:179], v[150:151], 0, s[24:25]
	v_pk_mul_f32 v[72:73], v[72:73], v[166:167]
	v_cvt_pk_bf16_f32 v172, v78, v79
	v_pk_mul_f32 v[70:71], v[70:71], v[66:67]
	v_cvt_pk_bf16_f32 v173, v80, v81
	v_pk_mul_f32 v[72:73], v[72:73], v[68:69]
	s_nop 0
	v_cvt_pk_bf16_f32 v174, v70, v71
	s_nop 0
	v_cvt_pk_bf16_f32 v175, v72, v73
	global_store_dwordx4 v[178:179], v[172:175], off nt
	v_pk_mul_f32 v[152:153], v[62:63], v[176:177] op_sel_hi:[1,0]
	v_pk_mul_f32 v[154:155], v[64:65], v[176:177] op_sel_hi:[1,0]
	v_pk_mul_f32 v[156:157], v[54:55], v[176:177] op_sel_hi:[1,0]
	v_pk_mul_f32 v[158:159], v[56:57], v[176:177] op_sel_hi:[1,0]
	v_exp_f32_e32 v152, v152
	v_exp_f32_e32 v153, v153
	v_exp_f32_e32 v154, v154
	v_exp_f32_e32 v155, v155
	v_pk_add_f32 v[152:153], v[152:153], 1.0 op_sel_hi:[1,0]
	v_exp_f32_e32 v156, v156
	v_exp_f32_e32 v157, v157
	v_pk_add_f32 v[154:155], v[154:155], 1.0 op_sel_hi:[1,0]
	v_exp_f32_e32 v158, v158
	v_exp_f32_e32 v159, v159
	v_rcp_f32_e32 v152, v152
	v_pk_add_f32 v[156:157], v[156:157], 1.0 op_sel_hi:[1,0]
	v_rcp_f32_e32 v153, v153
	v_rcp_f32_e32 v154, v154
	v_pk_add_f32 v[158:159], v[158:159], 1.0 op_sel_hi:[1,0]
	v_rcp_f32_e32 v155, v155
	v_rcp_f32_e32 v156, v156
	v_pk_mul_f32 v[62:63], v[62:63], v[152:153]
	v_rcp_f32_e32 v157, v157
	v_rcp_f32_e32 v158, v158
	v_pk_mul_f32 v[64:65], v[64:65], v[154:155]
	v_rcp_f32_e32 v159, v159
	v_pk_mul_f32 v[62:63], v[62:63], v[58:59]
	v_pk_mul_f32 v[54:55], v[54:55], v[156:157]
	v_pk_mul_f32 v[64:65], v[64:65], v[60:61]
	s_mov_b64 s[24:25], 0x6e000
	v_lshl_add_u64 v[150:151], v[178:179], 0, s[24:25]
	s_mov_b64 s[24:25], 0x16000
	v_pk_mul_f32 v[56:57], v[56:57], v[158:159]
	v_cvt_pk_bf16_f32 v168, v62, v63
	v_pk_mul_f32 v[54:55], v[54:55], v[50:51]
	v_cvt_pk_bf16_f32 v169, v64, v65
	v_pk_mul_f32 v[56:57], v[56:57], v[52:53]
	s_nop 0
	v_cvt_pk_bf16_f32 v170, v54, v55
	s_nop 0
	v_cvt_pk_bf16_f32 v171, v56, v57
	global_store_dwordx4 v[150:151], v[168:171], off nt
	v_pk_mul_f32 v[160:161], v[46:47], v[176:177] op_sel_hi:[1,0]
	v_pk_mul_f32 v[162:163], v[48:49], v[176:177] op_sel_hi:[1,0]
	v_pk_mul_f32 v[164:165], v[38:39], v[176:177] op_sel_hi:[1,0]
	v_pk_mul_f32 v[166:167], v[40:41], v[176:177] op_sel_hi:[1,0]
	v_exp_f32_e32 v160, v160
	v_exp_f32_e32 v161, v161
	v_exp_f32_e32 v162, v162
	v_exp_f32_e32 v163, v163
	v_pk_add_f32 v[160:161], v[160:161], 1.0 op_sel_hi:[1,0]
	v_exp_f32_e32 v164, v164
	v_exp_f32_e32 v165, v165
	v_pk_add_f32 v[162:163], v[162:163], 1.0 op_sel_hi:[1,0]
	v_exp_f32_e32 v166, v166
	v_exp_f32_e32 v167, v167
	v_rcp_f32_e32 v160, v160
	v_pk_add_f32 v[164:165], v[164:165], 1.0 op_sel_hi:[1,0]
	v_rcp_f32_e32 v161, v161
	v_rcp_f32_e32 v162, v162
	v_pk_add_f32 v[166:167], v[166:167], 1.0 op_sel_hi:[1,0]
	v_rcp_f32_e32 v163, v163
	v_rcp_f32_e32 v164, v164
	v_pk_mul_f32 v[46:47], v[46:47], v[160:161]
	v_rcp_f32_e32 v165, v165
	v_rcp_f32_e32 v166, v166
	v_pk_mul_f32 v[48:49], v[48:49], v[162:163]
	v_rcp_f32_e32 v167, v167
	v_pk_mul_f32 v[46:47], v[46:47], v[42:43]
	v_pk_mul_f32 v[38:39], v[38:39], v[164:165]
	v_pk_mul_f32 v[48:49], v[48:49], v[44:45]
	v_lshl_add_u64 v[178:179], v[150:151], 0, s[24:25]
	v_pk_mul_f32 v[40:41], v[40:41], v[166:167]
	v_cvt_pk_bf16_f32 v172, v46, v47
	v_pk_mul_f32 v[38:39], v[38:39], v[34:35]
	v_cvt_pk_bf16_f32 v173, v48, v49
	v_pk_mul_f32 v[40:41], v[40:41], v[36:37]
	s_nop 0
	v_cvt_pk_bf16_f32 v174, v38, v39
	s_nop 0
	v_cvt_pk_bf16_f32 v175, v40, v41
	global_store_dwordx4 v[178:179], v[172:175], off nt
	v_pk_mul_f32 v[152:153], v[30:31], v[176:177] op_sel_hi:[1,0]
	v_pk_mul_f32 v[154:155], v[32:33], v[176:177] op_sel_hi:[1,0]
	v_pk_mul_f32 v[156:157], v[22:23], v[176:177] op_sel_hi:[1,0]
	v_pk_mul_f32 v[158:159], v[24:25], v[176:177] op_sel_hi:[1,0]
	v_exp_f32_e32 v152, v152
	v_exp_f32_e32 v153, v153
	v_exp_f32_e32 v154, v154
	v_exp_f32_e32 v155, v155
	v_pk_add_f32 v[152:153], v[152:153], 1.0 op_sel_hi:[1,0]
	v_exp_f32_e32 v156, v156
	v_exp_f32_e32 v157, v157
	v_pk_add_f32 v[154:155], v[154:155], 1.0 op_sel_hi:[1,0]
	v_exp_f32_e32 v158, v158
	v_exp_f32_e32 v159, v159
	v_rcp_f32_e32 v152, v152
	v_pk_add_f32 v[156:157], v[156:157], 1.0 op_sel_hi:[1,0]
	v_rcp_f32_e32 v153, v153
	v_rcp_f32_e32 v154, v154
	v_pk_add_f32 v[158:159], v[158:159], 1.0 op_sel_hi:[1,0]
	v_rcp_f32_e32 v155, v155
	v_rcp_f32_e32 v156, v156
	v_pk_mul_f32 v[30:31], v[30:31], v[152:153]
	v_rcp_f32_e32 v157, v157
	v_rcp_f32_e32 v158, v158
	v_pk_mul_f32 v[32:33], v[32:33], v[154:155]
	v_rcp_f32_e32 v159, v159
	v_pk_mul_f32 v[30:31], v[30:31], v[26:27]
	v_pk_mul_f32 v[22:23], v[22:23], v[156:157]
	v_pk_mul_f32 v[32:33], v[32:33], v[28:29]
	v_lshl_add_u64 v[150:151], v[178:179], 0, s[24:25]
	v_pk_mul_f32 v[24:25], v[24:25], v[158:159]
	v_cvt_pk_bf16_f32 v168, v30, v31
	v_pk_mul_f32 v[22:23], v[22:23], v[18:19]
	v_cvt_pk_bf16_f32 v169, v32, v33
	v_pk_mul_f32 v[24:25], v[24:25], v[20:21]
	s_nop 0
	v_cvt_pk_bf16_f32 v170, v22, v23
	s_nop 0
	v_cvt_pk_bf16_f32 v171, v24, v25
	global_store_dwordx4 v[150:151], v[168:171], off nt
	v_pk_mul_f32 v[160:161], v[14:15], v[176:177] op_sel_hi:[1,0]
	v_pk_mul_f32 v[162:163], v[16:17], v[176:177] op_sel_hi:[1,0]
	v_pk_mul_f32 v[164:165], v[6:7], v[176:177] op_sel_hi:[1,0]
	v_pk_mul_f32 v[166:167], v[8:9], v[176:177] op_sel_hi:[1,0]
	v_exp_f32_e32 v160, v160
	v_exp_f32_e32 v161, v161
	v_exp_f32_e32 v162, v162
	v_exp_f32_e32 v163, v163
	v_pk_add_f32 v[160:161], v[160:161], 1.0 op_sel_hi:[1,0]
	v_exp_f32_e32 v164, v164
	v_exp_f32_e32 v165, v165
	v_pk_add_f32 v[162:163], v[162:163], 1.0 op_sel_hi:[1,0]
	v_exp_f32_e32 v166, v166
	v_exp_f32_e32 v167, v167
	v_rcp_f32_e32 v160, v160
	v_pk_add_f32 v[164:165], v[164:165], 1.0 op_sel_hi:[1,0]
	v_rcp_f32_e32 v161, v161
	v_rcp_f32_e32 v162, v162
	v_pk_add_f32 v[166:167], v[166:167], 1.0 op_sel_hi:[1,0]
	v_rcp_f32_e32 v163, v163
	v_rcp_f32_e32 v164, v164
	v_pk_mul_f32 v[14:15], v[14:15], v[160:161]
	v_rcp_f32_e32 v165, v165
	v_rcp_f32_e32 v166, v166
	v_pk_mul_f32 v[16:17], v[16:17], v[162:163]
	v_rcp_f32_e32 v167, v167
	v_pk_mul_f32 v[14:15], v[14:15], v[10:11]
	v_pk_mul_f32 v[6:7], v[6:7], v[164:165]
	v_pk_mul_f32 v[16:17], v[16:17], v[12:13]
	v_lshl_add_u64 v[178:179], v[150:151], 0, s[24:25]
	v_pk_mul_f32 v[8:9], v[8:9], v[166:167]
	v_cvt_pk_bf16_f32 v172, v14, v15
	v_pk_mul_f32 v[6:7], v[6:7], v[2:3]
	v_cvt_pk_bf16_f32 v173, v16, v17
	v_pk_mul_f32 v[8:9], v[8:9], v[4:5]
	s_nop 0
	v_cvt_pk_bf16_f32 v174, v6, v7
	s_nop 0
	v_cvt_pk_bf16_f32 v175, v8, v9
	global_store_dwordx4 v[178:179], v[172:175], off nt
	s_mov_b64 s[24:25], -1
	s_andn2_b64 vcc, exec, s[10:11]
	s_cbranch_vccnz .LBB0_780
; #define PG8_BAR __builtin_amdgcn_s_barrier()
; template <class Epi, class Sched, bool ALIGN_EPI = false, bool SP2 = false>
; __device__ __forceinline__ void gemm_phase(PG8_LAS unsigned char* lds, const Gemm g, const Sched& S, const Epi& E) {
;     ...
;         if (!has_next) break;
; #pragma unroll
;         for (int a = 0; a < 2; ++a)
; #pragma unroll
;             for (int b = 0; b < 2; ++b)
; #pragma unroll
;                 for (int m = 0; m < 4; ++m)
; #pragma unroll
;                     for (int n = 0; n < 2; ++n) acc[a][b][m][n] = (f32x4){0.f, 0.f, 0.f, 0.f};
;         cur = nxt; cA = nA; cB = nB; ++ui;
;         if constexpr (ALIGN_EPI) { if (wr == 1) PG8_BAR; }
	s_andn2_b64 vcc, exec, s[12:13]
	s_cbranch_vccnz .LBB0_779
	s_barrier
	s_branch .LBB0_779
